# v17 + NSA staging block straight-line (s_cselect buffer select, one set of ds_writes, no branch ladder), saddr-based K/V tile loads, dead descriptor decode removed
# speedup vs baseline: 1.0071x; 1.0071x over previous
; DI f32x16 mma32(bf16x8 a, bf16x8 b, f32x16 c) { return __builtin_amdgcn_mfma_f32_32x32x16_bf16(a, b, c, 0, 0, 0); }
; DI bf16x8 packp(const f32x16& x, const int h8) { v4u p; p.x = pk2(x[h8 + 0], x[h8 + 1]); p.y = pk2(x[h8 + 2], x[h8 + 3]); p.z = pk2(x[h8 + 4], x[h8 + 5]); p.w = pk2(x[h8 + 6], x[h8 + 7]); return __builtin_bit_cast(bf16x8, p); }
; DI void nsa_item(KA a, LAS unsigned char* lds, const int it) {
;     ...
;         f32x16 ot[2] = {ZERO16, ZERO16};
; #pragma unroll
;         for (int sp = 0; sp < 8; ++sp) { const bf16x8 pf = packp(st[sp >> 1], 8 * (sp & 1));
; #pragma unroll
;             for (int dh = 0; dh < 2; ++dh) ot[dh] = mma32(vfrag(VT, 32 * dh + r, sp, hf), pf, ot[dh]); }
;         of[0] = ot[0] * g0; of[1] = ot[1] * g0;
.LBB0_794:
	v_add_f32_e32 v33, 1.0, v33
	v_rcp_f32_e32 v34, v33
	s_andn2_b64 vcc, exec, s[0:1]
	v_readlane_b32 s90, v254, 47
	v_pk_mul_f32 v[124:125], v[34:35], v[30:31] op_sel_hi:[0,1]
	v_pk_mul_f32 v[120:121], v[34:35], v[28:29] op_sel_hi:[0,1]
	v_pk_mul_f32 v[116:117], v[34:35], v[26:27] op_sel_hi:[0,1]
	v_pk_mul_f32 v[112:113], v[34:35], v[24:25] op_sel_hi:[0,1]
	v_pk_mul_f32 v[108:109], v[34:35], v[22:23] op_sel_hi:[0,1]
	v_pk_mul_f32 v[104:105], v[34:35], v[20:21] op_sel_hi:[0,1]
	v_pk_mul_f32 v[100:101], v[34:35], v[18:19] op_sel_hi:[0,1]
	v_pk_mul_f32 v[96:97], v[34:35], v[16:17] op_sel_hi:[0,1]
	v_pk_mul_f32 v[122:123], v[34:35], v[14:15] op_sel_hi:[0,1]
	v_pk_mul_f32 v[118:119], v[34:35], v[12:13] op_sel_hi:[0,1]
	v_pk_mul_f32 v[114:115], v[34:35], v[10:11] op_sel_hi:[0,1]
	v_pk_mul_f32 v[110:111], v[34:35], v[8:9] op_sel_hi:[0,1]
	v_pk_mul_f32 v[106:107], v[34:35], v[6:7] op_sel_hi:[0,1]
	v_pk_mul_f32 v[102:103], v[34:35], v[4:5] op_sel_hi:[0,1]
	v_pk_mul_f32 v[98:99], v[34:35], v[2:3] op_sel_hi:[0,1]
	v_pk_mul_f32 v[94:95], v[34:35], v[0:1] op_sel_hi:[0,1]
	v_mov_b32_e32 v31, 0
	s_cbranch_vccnz .LBB0_811
; #define LAS __attribute__((address_space(3)))
; #define NSA_STORE(Kb, Vb) do { *(LAS v4u*)((Kb) + skey * PA + 8 * sch) = kreg; LAS unsigned* d0_ = (LAS unsigned*)((Vb) + (4 * sdg) * PV + vpos(2 * skp)); \
;         d0_[0] = (vr0.x & 0xffffu) | (vr1.x << 16); d0_[PV / 2] = (vr0.x >> 16) | (vr1.x & 0xffff0000u); d0_[PV] = (vr0.y & 0xffffu) | (vr1.y << 16); d0_[3 * PV / 2] = (vr0.y >> 16) | (vr1.y & 0xffff0000u); } while (0)
; DI void nsa_item(KA a, LAS unsigned char* lds, const int it) {
;     ...
;     const int skey = tid >> 3, sch = tid & 7, sdg = tid & 15, skp = tid >> 4;
;     ...
;     const unsigned mysel = SELM[tql]; const int n = *NLIST;
;     LAS bf16* Kt1 = (LAS bf16*)(lds + NSA_KT1); LAS bf16* VT1 = (LAS bf16*)(lds + NSA_VT1);
;     NSA_STORE(Kt, VT);
;     NSA_LOAD(LIST[1]);
;     __syncthreads();
;     float m_ref = 0.f, l_run = 0.f; f32x16 ot[2] = {ZERO16, ZERO16}; int curtype = 0;
	v_cmp_gt_u32_e64 s[0:1], v92, v135
	v_or_b32_e32 v0, 2, v92
	s_sub_i32 s85, 23, s40
	v_writelane_b32 v254, s0, 49
	s_mov_b32 s87, 0
	s_mov_b32 s88, 0
	v_writelane_b32 v254, s1, 50
	v_cmp_le_u32_e64 s[0:1], v92, v135
	v_mov_b32_e32 v137, 0
	v_mov_b32_e32 v16, 0
	v_writelane_b32 v254, s0, 51
	s_nop 1
	v_writelane_b32 v254, s1, 52
	v_cmp_ge_u32_e64 s[0:1], v92, v135
	s_nop 1
	v_writelane_b32 v254, s0, 53
	s_nop 1
	v_writelane_b32 v254, s1, 54
	v_cmp_lt_u32_e64 s[0:1], v92, v135
	s_nop 1
	v_writelane_b32 v254, s0, 55
	s_nop 1
	v_writelane_b32 v254, s1, 56
	v_cmp_gt_u32_e64 s[0:1], v0, v135
	s_nop 1
	v_writelane_b32 v254, s0, 57
	s_nop 1
	v_writelane_b32 v254, s1, 58
	v_cmp_le_u32_e64 s[0:1], v0, v135
	v_or_b32_e32 v0, 3, v92
	s_nop 0
	v_writelane_b32 v254, s0, 59
	s_nop 1
	v_writelane_b32 v254, s1, 60
	v_cmp_gt_u32_e64 s[0:1], v0, v135
	s_nop 1
	v_writelane_b32 v254, s0, 61
	s_nop 1
	v_writelane_b32 v254, s1, 62
	v_cmp_le_u32_e64 s[0:1], v0, v135
	v_or_b32_e32 v0, 8, v92
	s_nop 0
	v_writelane_b32 v254, s0, 63
	s_nop 0
	v_readlane_b32 s86, v254, 13
	v_writelane_b32 v245, s1, 0
	v_cmp_gt_u32_e64 s[0:1], v0, v135
	s_nop 1
	v_writelane_b32 v245, s0, 1
	s_nop 1
	v_writelane_b32 v245, s1, 2
	v_cmp_le_u32_e64 s[0:1], v0, v135
	v_or_b32_e32 v0, 9, v92
	s_nop 0
	v_writelane_b32 v245, s0, 3
	s_nop 1
	v_writelane_b32 v245, s1, 4
	v_cmp_gt_u32_e64 s[0:1], v0, v135
	s_nop 1
	v_writelane_b32 v245, s0, 5
	s_nop 1
	v_writelane_b32 v245, s1, 6
	v_cmp_le_u32_e64 s[0:1], v0, v135
	v_or_b32_e32 v0, 10, v92
	s_nop 0
	v_writelane_b32 v245, s0, 7
	s_nop 1
	v_writelane_b32 v245, s1, 8
	v_cmp_gt_u32_e64 s[0:1], v0, v135
	s_nop 1
	v_writelane_b32 v245, s0, 9
	s_nop 1
	v_writelane_b32 v245, s1, 10
	v_cmp_le_u32_e64 s[0:1], v0, v135
	v_or_b32_e32 v0, 11, v92
	s_nop 0
	v_writelane_b32 v245, s0, 11
	s_nop 1
	v_writelane_b32 v245, s1, 12
	v_cmp_gt_u32_e64 s[0:1], v0, v135
	s_nop 1
	v_writelane_b32 v245, s0, 13
	s_nop 1
	v_writelane_b32 v245, s1, 14
	v_cmp_le_u32_e64 s[0:1], v0, v135
	v_or_b32_e32 v0, 16, v92
	s_nop 0
	v_writelane_b32 v245, s0, 15
	s_nop 1
	v_writelane_b32 v245, s1, 16
	v_cmp_gt_u32_e64 s[0:1], v0, v135
	s_nop 1
	v_writelane_b32 v245, s0, 17
	s_nop 1
	v_writelane_b32 v245, s1, 18
	v_cmp_le_u32_e64 s[0:1], v0, v135
	v_or_b32_e32 v0, 17, v92
	s_nop 0
	v_writelane_b32 v245, s0, 19
	s_nop 1
	v_writelane_b32 v245, s1, 20
	v_cmp_gt_u32_e64 s[0:1], v0, v135
	s_nop 1
	v_writelane_b32 v245, s0, 21
	s_nop 1
	v_writelane_b32 v245, s1, 22
	v_cmp_le_u32_e64 s[0:1], v0, v135
	v_or_b32_e32 v0, 18, v92
	s_nop 0
	v_writelane_b32 v245, s0, 23
	s_nop 1
	v_writelane_b32 v245, s1, 24
	v_cmp_gt_u32_e64 s[0:1], v0, v135
	s_nop 1
	v_writelane_b32 v245, s0, 25
	s_nop 1
	v_writelane_b32 v245, s1, 26
	v_cmp_le_u32_e64 s[0:1], v0, v135
	v_or_b32_e32 v0, 19, v92
	s_nop 0
	v_writelane_b32 v245, s0, 27
	s_nop 1
	v_writelane_b32 v245, s1, 28
	v_cmp_gt_u32_e64 s[0:1], v0, v135
	s_nop 1
	v_writelane_b32 v245, s0, 29
	s_nop 1
	v_writelane_b32 v245, s1, 30
	v_cmp_le_u32_e64 s[0:1], v0, v135
	v_or_b32_e32 v0, 24, v92
	s_nop 0
	v_writelane_b32 v245, s0, 31
	s_nop 1
	v_writelane_b32 v245, s1, 32
	v_cmp_gt_u32_e64 s[0:1], v0, v135
	s_nop 1
	v_writelane_b32 v245, s0, 33
	s_nop 1
	v_writelane_b32 v245, s1, 34
	v_cmp_le_u32_e64 s[0:1], v0, v135
	v_or_b32_e32 v0, 25, v92
	v_cmp_gt_u32_e64 s[92:93], v0, v135
	v_cmp_le_u32_e64 s[94:95], v0, v135
	v_or_b32_e32 v0, 26, v92
	v_cmp_gt_u32_e64 s[96:97], v0, v135
	v_cmp_le_u32_e64 s[6:7], v0, v135
	v_or_b32_e32 v0, 27, v92
	v_cmp_gt_u32_e64 s[8:9], v0, v135
	v_cmp_le_u32_e64 s[10:11], v0, v135
	v_or_b32_e32 v0, 32, v92
	v_cmp_gt_u32_e64 s[12:13], v0, v135
	v_cmp_le_u32_e64 s[14:15], v0, v135
	v_or_b32_e32 v0, 33, v92
	v_cmp_gt_u32_e64 s[16:17], v0, v135
	v_cmp_le_u32_e64 s[18:19], v0, v135
	v_or_b32_e32 v0, 34, v92
	v_cmp_gt_u32_e64 s[20:21], v0, v135
	v_cmp_le_u32_e64 s[22:23], v0, v135
	v_or_b32_e32 v0, 35, v92
	v_cmp_gt_u32_e64 s[24:25], v0, v135
	v_cmp_le_u32_e64 s[26:27], v0, v135
	v_or_b32_e32 v0, 40, v92
	v_cmp_gt_u32_e64 s[28:29], v0, v135
	v_cmp_le_u32_e64 s[30:31], v0, v135
	v_or_b32_e32 v0, 41, v92
	v_cmp_gt_u32_e64 s[34:35], v0, v135
	v_cmp_le_u32_e64 s[36:37], v0, v135
	v_or_b32_e32 v0, 42, v92
	v_cmp_gt_u32_e64 s[38:39], v0, v135
	v_cmp_le_u32_e64 s[4:5], v0, v135
	v_or_b32_e32 v0, 43, v92
	v_writelane_b32 v245, s0, 35
	v_cmp_gt_u32_e64 s[40:41], v0, v135
	v_cmp_le_u32_e64 s[2:3], v0, v135
	v_or_b32_e32 v0, 48, v92
	v_writelane_b32 v245, s1, 36
	v_cmp_gt_u32_e64 s[0:1], v0, v135
	v_cmp_le_u32_e64 s[42:43], v0, v135
	v_or_b32_e32 v0, 49, v92
	v_cmp_gt_u32_e64 s[44:45], v0, v135
	v_cmp_le_u32_e64 s[46:47], v0, v135
	v_or_b32_e32 v0, 50, v92
	v_cmp_gt_u32_e64 s[48:49], v0, v135
	v_cmp_le_u32_e64 s[50:51], v0, v135
	v_or_b32_e32 v0, 51, v92
	v_cmp_gt_u32_e64 s[52:53], v0, v135
	v_cmp_le_u32_e64 s[54:55], v0, v135
	v_or_b32_e32 v0, 56, v92
	v_cmp_gt_u32_e64 s[56:57], v0, v135
	v_cmp_le_u32_e64 s[58:59], v0, v135
	v_or_b32_e32 v0, 57, v92
	v_cmp_gt_u32_e64 s[60:61], v0, v135
	v_cmp_le_u32_e64 s[62:63], v0, v135
	v_or_b32_e32 v0, 58, v92
	v_cmp_gt_u32_e64 s[64:65], v0, v135
	v_cmp_le_u32_e64 s[66:67], v0, v135
	v_or_b32_e32 v0, 59, v92
	v_cmp_gt_u32_e64 s[68:69], v0, v135
	v_cmp_le_u32_e64 s[70:71], v0, v135
	v_mov_b32_e32 v135, 0
	v_mov_b32_e32 v0, 0
	v_mov_b32_e32 v1, v135
	v_mov_b32_e32 v2, v135
	v_mov_b32_e32 v3, v135
	v_mov_b32_e32 v4, v135
	v_mov_b32_e32 v5, v135
	v_mov_b32_e32 v6, v135
	v_mov_b32_e32 v7, v135
	v_mov_b32_e32 v8, v135
	v_mov_b32_e32 v9, v135
	v_mov_b32_e32 v10, v135
	v_mov_b32_e32 v11, v135
	v_mov_b32_e32 v12, v135
	v_mov_b32_e32 v13, v135
	v_mov_b32_e32 v14, v135
	v_mov_b32_e32 v15, v135
	v_mov_b32_e32 v17, v135
	v_mov_b32_e32 v18, v135
	v_mov_b32_e32 v19, v135
	v_mov_b32_e32 v20, v135
	v_mov_b32_e32 v21, v135
	v_mov_b32_e32 v22, v135
	v_mov_b32_e32 v23, v135
	v_mov_b32_e32 v24, v135
	v_mov_b32_e32 v25, v135
	v_mov_b32_e32 v26, v135
	v_mov_b32_e32 v27, v135
	v_mov_b32_e32 v28, v135
	v_mov_b32_e32 v29, v135
	v_mov_b32_e32 v30, v135
	v_mov_b32_e32 v31, v135
	s_movk_i32 s74, 0x1c00
	v_mad_u32_u24 v190, v132, s74, v192
	v_mad_u32_u24 v251, v133, s74, v88
	v_add_u32_e32 v241, 0x1c00, v251
	v_add3_u32 v231, 0, v90, v130
	s_movk_i32 s74, 0x4800
	v_add3_u32 v230, s74, v90, v131
	ds_read_b128 v[170:173], v231 offset:64
	ds_read_b128 v[178:181], v231 offset:4608
	ds_read_b128 v[182:185], v231 offset:4640
	ds_read_b128 v[186:189], v231 offset:4672
	ds_read_b128 v[206:209], v231 offset:4704
	ds_read_b128 v[174:177], v231 offset:96
	s_add_i32 s74, s86, -8
	v_mov_b32_e32 v191, s74
	ds_read_b32 v191, v191
	v_mov_b32_e32 v250, s86
	ds_read_b32 v250, v250
	ds_read_b128 v[210:213], v230
	ds_read_b128 v[218:221], v230 offset:8704
	ds_read_b128 v[222:225], v230 offset:8736
	ds_read_b128 v[214:217], v230 offset:32
	ds_read_b128 v[226:229], v230 offset:64
	ds_read_b128 v[152:155], v230 offset:8768
	ds_read_b128 v[246:249], v230 offset:96
	ds_read_b128 v[144:147], v231
	ds_read_b128 v[148:151], v231 offset:32

; #define LAS __attribute__((address_space(3)))
; DI f32x16 mma32(bf16x8 a, bf16x8 b, f32x16 c) { return __builtin_amdgcn_mfma_f32_32x32x16_bf16(a, b, c, 0, 0, 0); }
; DI int crow(int i, int hf) { return (i & 3) + 8 * (i >> 2) + 4 * hf; }
; DI void nsa_item(KA a, LAS unsigned char* lds, const int it) {
;     ...
;         const int desc = LIST[i]; const int ty = desc >> 8, j = desc & 255;
;         const LAS bf16* Kc = (i & 1) ? Kt1 : Kt; const LAS bf16* Vc = (i & 1) ? VT1 : VT;
;         if (ty != curtype) { const float lt = l_run + __shfl_xor(l_run, 32); const float sc = g1 / lt; of[0] += ot[0] * sc; of[1] += ot[1] * sc; ot[0] = ZERO16; ot[1] = ZERO16; m_ref = 0.f; l_run = 0.f; curtype = ty; }
;         const bool rowoff = (ty == 0) && (((mysel >> j) & 1u) == 0u);
;         const int mode = (j == qb) ? 1 : ((ty == 1 && j == qb - 8) ? 2 : 0);
;         const float init = rowoff ? -INFINITY : -m_ref;
;         f32x16 st[2];
; #pragma unroll
;         for (int i2 = 0; i2 < 16; ++i2) { st[0][i2] = init; st[1][i2] = init; }
; #pragma unroll
;         for (int kt = 0; kt < 2; ++kt)
; #pragma unroll
;             for (int s = 0; s < 4; ++s) { const bf16x8 af = *(const LAS bf16x8*)(Kc + (32 * kt + r) * PA + 16 * s + 8 * hf); st[kt] = mma32(af, bq[s], st[kt]); }
;         if (mode != 0) {
; #pragma unroll
;             for (int kt = 0; kt < 2; ++kt)
; #pragma unroll
;                 for (int i2 = 0; i2 < 16; ++i2) { const int kl = 32 * kt + crow(i2, hf); const bool bad = rowoff || (mode == 1 && kl > tql) || (mode == 2 && kl <= tql); st[kt][i2] = bad ? -INFINITY : st[kt][i2]; }
.LBB0_798:
	s_and_b32 s83, s78, 0xff
	s_cmpk_lt_u32 s78, 0x100
	s_cselect_b64 s[80:81], -1, 0
	s_lshl_b32 s78, 1, s78
	v_and_b32_e32 v32, s78, v141
	v_cmp_eq_u32_e32 vcc, 0, v32
	s_and_b64 s[78:79], s[80:81], vcc
	v_cndmask_b32_e64 v32, -v137, v240, s[78:79]
	v_mov_b32_e32 v33, v32
	v_mov_b32_e32 v34, v32
	v_mov_b32_e32 v35, v32
	v_mov_b32_e32 v36, v32
	v_mov_b32_e32 v37, v32
	v_mov_b32_e32 v38, v32
	v_mov_b32_e32 v39, v32
	v_mov_b32_e32 v40, v32
	v_mov_b32_e32 v41, v32
	v_mov_b32_e32 v42, v32
	v_mov_b32_e32 v43, v32
	v_mov_b32_e32 v44, v32
	v_mov_b32_e32 v45, v32
	v_mov_b32_e32 v46, v32
	v_mov_b32_e32 v47, v32
	s_cmp_eq_u32 s83, s90
	s_cselect_b64 s[80:81], -1, 0
	s_nop 0
	v_mfma_f32_32x32x16_bf16 v[48:63], v[170:173], v[68:71], v[32:47]
	s_cmp_eq_u32 s83, s85
	s_cselect_b64 vcc, -1, 0
	s_cmp_eq_u32 s82, 1
	s_cselect_b64 s[82:83], -1, 0
	s_and_b64 s[82:83], s[82:83], vcc
	s_or_b64 vcc, s[80:81], s[82:83]
	s_andn2_b64 vcc, exec, vcc
	v_mfma_f32_32x32x16_bf16 v[32:47], v[178:181], v[72:75], v[32:47]
	v_mfma_f32_32x32x16_bf16 v[32:47], v[182:185], v[64:67], v[32:47]
	v_mfma_f32_32x32x16_bf16 v[32:47], v[186:189], v[68:71], v[32:47]
	v_mfma_f32_32x32x16_bf16 v[32:47], v[206:209], v[76:79], v[32:47]
	v_mfma_f32_32x32x16_bf16 v[48:63], v[174:177], v[76:79], v[48:63]
	s_waitcnt lgkmcnt(1)
	v_mfma_f32_32x32x16_bf16 v[48:63], v[144:147], v[72:75], v[48:63]
	s_waitcnt lgkmcnt(0)
	v_mfma_f32_32x32x16_bf16 v[48:63], v[148:151], v[64:67], v[48:63]
	ds_read_b128 v[148:151], v230 offset:8800
	s_cbranch_vccnz .LBB0_800
	s_xor_b64 vcc, s[80:81], -1
	s_and_b64 s[82:83], vcc, s[82:83]
	v_readlane_b32 vcc_lo, v254, 49
	v_readlane_b32 vcc_hi, v254, 50
	s_mov_b32 s89, s91
	v_readlane_b32 s90, v254, 51
	s_and_b64 vcc, s[80:81], vcc
	v_readlane_b32 s91, v254, 52
	s_or_b64 vcc, s[78:79], vcc
	s_and_b64 s[90:91], s[82:83], s[90:91]
	s_or_b64 vcc, vcc, s[90:91]
	v_readlane_b32 s90, v254, 53
	v_cndmask_b32_e32 v48, v48, v240, vcc
	v_readlane_b32 s91, v254, 54
	v_readlane_b32 vcc_lo, v254, 55
	s_and_b64 s[90:91], s[80:81], s[90:91]
	v_readlane_b32 vcc_hi, v254, 56
	s_or_b64 s[90:91], s[78:79], s[90:91]
	s_and_b64 vcc, s[82:83], vcc
	s_or_b64 vcc, s[90:91], vcc
	v_readlane_b32 s90, v254, 57
	v_cndmask_b32_e32 v49, v49, v240, vcc
	v_readlane_b32 s91, v254, 58
	v_readlane_b32 vcc_lo, v254, 59
	s_and_b64 s[90:91], s[80:81], s[90:91]
	v_readlane_b32 vcc_hi, v254, 60
	s_or_b64 s[90:91], s[78:79], s[90:91]
	s_and_b64 vcc, s[82:83], vcc
	s_or_b64 vcc, s[90:91], vcc
	v_readlane_b32 s90, v254, 61
	v_cndmask_b32_e32 v50, v50, v240, vcc
	v_readlane_b32 s91, v254, 62
	v_readlane_b32 vcc_lo, v254, 63
	s_and_b64 s[90:91], s[80:81], s[90:91]
	v_readlane_b32 vcc_hi, v245, 0
	s_or_b64 s[90:91], s[78:79], s[90:91]
	s_and_b64 vcc, s[82:83], vcc
	s_or_b64 vcc, s[90:91], vcc
	v_readlane_b32 s90, v245, 1
	v_cndmask_b32_e32 v51, v51, v240, vcc
	v_readlane_b32 s91, v245, 2
	v_readlane_b32 vcc_lo, v245, 3
	s_and_b64 s[90:91], s[80:81], s[90:91]
	v_readlane_b32 vcc_hi, v245, 4
	s_or_b64 s[90:91], s[78:79], s[90:91]
	s_and_b64 vcc, s[82:83], vcc
	s_or_b64 vcc, s[90:91], vcc
	v_readlane_b32 s90, v245, 5
	v_cndmask_b32_e32 v52, v52, v240, vcc
	v_readlane_b32 s91, v245, 6
	v_readlane_b32 vcc_lo, v245, 7
	s_and_b64 s[90:91], s[80:81], s[90:91]
	v_readlane_b32 vcc_hi, v245, 8
	s_or_b64 s[90:91], s[78:79], s[90:91]
	s_and_b64 vcc, s[82:83], vcc
	s_or_b64 vcc, s[90:91], vcc
	v_readlane_b32 s90, v245, 9
	v_cndmask_b32_e32 v53, v53, v240, vcc
	v_readlane_b32 s91, v245, 10
	v_readlane_b32 vcc_lo, v245, 11
	s_and_b64 s[90:91], s[80:81], s[90:91]
	v_readlane_b32 vcc_hi, v245, 12
	s_or_b64 s[90:91], s[78:79], s[90:91]
	s_and_b64 vcc, s[82:83], vcc
	s_or_b64 vcc, s[90:91], vcc
	v_readlane_b32 s90, v245, 13
	v_cndmask_b32_e32 v54, v54, v240, vcc
	v_readlane_b32 s91, v245, 14
	v_readlane_b32 vcc_lo, v245, 15
	s_and_b64 s[90:91], s[80:81], s[90:91]
	v_readlane_b32 vcc_hi, v245, 16
	s_or_b64 s[90:91], s[78:79], s[90:91]
	s_and_b64 vcc, s[82:83], vcc
	s_or_b64 vcc, s[90:91], vcc
	v_readlane_b32 s90, v245, 17
	v_cndmask_b32_e32 v55, v55, v240, vcc
	v_readlane_b32 s91, v245, 18
	v_readlane_b32 vcc_lo, v245, 19
	s_and_b64 s[90:91], s[80:81], s[90:91]
	v_readlane_b32 vcc_hi, v245, 20
	s_or_b64 s[90:91], s[78:79], s[90:91]
	s_and_b64 vcc, s[82:83], vcc
	s_or_b64 vcc, s[90:91], vcc
	v_readlane_b32 s90, v245, 21
	v_cndmask_b32_e32 v56, v56, v240, vcc
	v_readlane_b32 s91, v245, 22
	v_readlane_b32 vcc_lo, v245, 23
	s_and_b64 s[90:91], s[80:81], s[90:91]
	v_readlane_b32 vcc_hi, v245, 24
	s_or_b64 s[90:91], s[78:79], s[90:91]
	s_and_b64 vcc, s[82:83], vcc
	s_or_b64 vcc, s[90:91], vcc
	v_readlane_b32 s90, v245, 25
	v_cndmask_b32_e32 v57, v57, v240, vcc
	v_readlane_b32 s91, v245, 26
	v_readlane_b32 vcc_lo, v245, 27
	s_and_b64 s[90:91], s[80:81], s[90:91]
	v_readlane_b32 vcc_hi, v245, 28
	s_or_b64 s[90:91], s[78:79], s[90:91]
	s_and_b64 vcc, s[82:83], vcc
	s_or_b64 vcc, s[90:91], vcc
	v_readlane_b32 s90, v245, 29
	v_cndmask_b32_e32 v58, v58, v240, vcc
	v_readlane_b32 s91, v245, 30
	v_readlane_b32 vcc_lo, v245, 31
	s_and_b64 s[90:91], s[80:81], s[90:91]
	v_readlane_b32 vcc_hi, v245, 32
	s_or_b64 s[90:91], s[78:79], s[90:91]
	s_and_b64 vcc, s[82:83], vcc
	s_or_b64 vcc, s[90:91], vcc
	v_readlane_b32 s90, v245, 33
	v_cndmask_b32_e32 v59, v59, v240, vcc
	v_readlane_b32 s91, v245, 34
; #define NSA_STORE(Kb, Vb) do { *(LAS v4u*)((Kb) + skey * PA + 8 * sch) = kreg; LAS unsigned* d0_ = (LAS unsigned*)((Vb) + (4 * sdg) * PV + vpos(2 * skp)); \
;         d0_[0] = (vr0.x & 0xffffu) | (vr1.x << 16); d0_[PV / 2] = (vr0.x >> 16) | (vr1.x & 0xffff0000u); d0_[PV] = (vr0.y & 0xffffu) | (vr1.y << 16); d0_[3 * PV / 2] = (vr0.y >> 16) | (vr1.y & 0xffff0000u); } while (0)
; DI void nsa_item(KA a, LAS unsigned char* lds, const int it) {
;     ...
;         if (i + 1 < n) { if (i & 1) NSA_STORE(Kt, VT); else NSA_STORE(Kt1, VT1); if (i + 2 < n) NSA_LOAD(LIST[i + 2]); }
	v_readlane_b32 vcc_lo, v245, 35
	s_and_b64 s[90:91], s[80:81], s[90:91]
	v_readlane_b32 vcc_hi, v245, 36
	s_or_b64 s[90:91], s[78:79], s[90:91]
	s_and_b64 vcc, s[82:83], vcc
	s_or_b64 vcc, s[90:91], vcc
	s_and_b64 s[90:91], s[80:81], s[92:93]
	v_cndmask_b32_e32 v60, v60, v240, vcc
	s_or_b64 s[90:91], s[78:79], s[90:91]
	s_and_b64 vcc, s[82:83], s[94:95]
	s_or_b64 vcc, s[90:91], vcc
	s_and_b64 s[90:91], s[80:81], s[96:97]
	v_cndmask_b32_e32 v61, v61, v240, vcc
	s_or_b64 s[90:91], s[78:79], s[90:91]
	s_and_b64 vcc, s[82:83], s[6:7]
	s_or_b64 vcc, s[90:91], vcc
	s_and_b64 s[90:91], s[80:81], s[8:9]
	v_cndmask_b32_e32 v62, v62, v240, vcc
	s_or_b64 s[90:91], s[78:79], s[90:91]
	s_and_b64 vcc, s[82:83], s[10:11]
	s_or_b64 vcc, s[90:91], vcc
	s_and_b64 s[90:91], s[80:81], s[12:13]
	v_cndmask_b32_e32 v63, v63, v240, vcc
	s_or_b64 s[90:91], s[78:79], s[90:91]
	s_and_b64 vcc, s[82:83], s[14:15]
	s_or_b64 vcc, s[90:91], vcc
	s_and_b64 s[90:91], s[80:81], s[16:17]
	v_cndmask_b32_e32 v32, v32, v240, vcc
	s_or_b64 s[90:91], s[78:79], s[90:91]
	s_and_b64 vcc, s[82:83], s[18:19]
	s_or_b64 vcc, s[90:91], vcc
	s_and_b64 s[90:91], s[80:81], s[20:21]
	v_cndmask_b32_e32 v33, v33, v240, vcc
	s_or_b64 s[90:91], s[78:79], s[90:91]
	s_and_b64 vcc, s[82:83], s[22:23]
	s_or_b64 vcc, s[90:91], vcc
	s_and_b64 s[90:91], s[80:81], s[24:25]
	v_cndmask_b32_e32 v34, v34, v240, vcc
	s_or_b64 s[90:91], s[78:79], s[90:91]
	s_and_b64 vcc, s[82:83], s[26:27]
	s_or_b64 vcc, s[90:91], vcc
	s_and_b64 s[90:91], s[80:81], s[28:29]
	v_cndmask_b32_e32 v35, v35, v240, vcc
	s_or_b64 s[90:91], s[78:79], s[90:91]
	s_and_b64 vcc, s[82:83], s[30:31]
	s_or_b64 vcc, s[90:91], vcc
	s_and_b64 s[90:91], s[80:81], s[34:35]
	v_cndmask_b32_e32 v36, v36, v240, vcc
	s_or_b64 s[90:91], s[78:79], s[90:91]
	s_and_b64 vcc, s[82:83], s[36:37]
	s_or_b64 vcc, s[90:91], vcc
	s_and_b64 s[90:91], s[80:81], s[38:39]
	v_cndmask_b32_e32 v37, v37, v240, vcc
	s_or_b64 s[90:91], s[78:79], s[90:91]
	s_and_b64 vcc, s[82:83], s[4:5]
	s_or_b64 vcc, s[90:91], vcc
	s_and_b64 s[90:91], s[80:81], s[40:41]
	v_cndmask_b32_e32 v38, v38, v240, vcc
	s_or_b64 s[90:91], s[78:79], s[90:91]
	s_and_b64 vcc, s[82:83], s[2:3]
	s_or_b64 vcc, s[90:91], vcc
	s_and_b64 s[90:91], s[80:81], s[0:1]
	v_cndmask_b32_e32 v39, v39, v240, vcc
	s_or_b64 s[90:91], s[78:79], s[90:91]
	s_and_b64 vcc, s[82:83], s[42:43]
	s_or_b64 vcc, s[90:91], vcc
	s_and_b64 s[90:91], s[80:81], s[44:45]
	v_cndmask_b32_e32 v40, v40, v240, vcc
	s_or_b64 s[90:91], s[78:79], s[90:91]
	s_and_b64 vcc, s[82:83], s[46:47]
	s_or_b64 vcc, s[90:91], vcc
	s_and_b64 s[90:91], s[80:81], s[48:49]
	v_cndmask_b32_e32 v41, v41, v240, vcc
	s_or_b64 s[90:91], s[78:79], s[90:91]
	s_and_b64 vcc, s[82:83], s[50:51]
	s_or_b64 vcc, s[90:91], vcc
	s_and_b64 s[90:91], s[80:81], s[52:53]
	v_cndmask_b32_e32 v42, v42, v240, vcc
	s_or_b64 s[90:91], s[78:79], s[90:91]
	s_and_b64 vcc, s[82:83], s[54:55]
	s_or_b64 vcc, s[90:91], vcc
	s_and_b64 s[90:91], s[80:81], s[56:57]
	v_cndmask_b32_e32 v43, v43, v240, vcc
	s_or_b64 s[90:91], s[78:79], s[90:91]
	s_and_b64 vcc, s[82:83], s[58:59]
	s_or_b64 vcc, s[90:91], vcc
	s_and_b64 s[90:91], s[80:81], s[60:61]
	v_cndmask_b32_e32 v44, v44, v240, vcc
	s_or_b64 s[90:91], s[78:79], s[90:91]
	s_and_b64 vcc, s[82:83], s[62:63]
	s_or_b64 vcc, s[90:91], vcc
	s_and_b64 s[90:91], s[80:81], s[64:65]
	v_cndmask_b32_e32 v45, v45, v240, vcc
	s_or_b64 s[90:91], s[78:79], s[90:91]
	s_and_b64 vcc, s[82:83], s[66:67]
	s_and_b64 s[80:81], s[80:81], s[68:69]
	s_or_b64 vcc, s[90:91], vcc
	s_or_b64 s[78:79], s[78:79], s[80:81]
	s_and_b64 s[80:81], s[82:83], s[70:71]
	v_cndmask_b32_e32 v46, v46, v240, vcc
	s_or_b64 vcc, s[78:79], s[80:81]
	v_readlane_b32 s90, v254, 47
	s_mov_b32 s91, s89
	v_cndmask_b32_e32 v47, v47, v240, vcc
.LBB0_800:
	s_add_i32 s79, s87, 1
	s_cmp_ge_i32 s79, s84
	s_cbranch_scc1 .Lnsa_rsskip0
	s_bitcmp1_b32 s87, 0
	s_cselect_b32 s74, 0, 0x9000
	s_cselect_b32 s75, 0, 0x6c00
	v_add_u32_e32 v144, s74, v142
	v_add_u32_e32 v191, s75, v138
	s_mov_b32 s77, 0xffff0000
	s_waitcnt vmcnt(1)
	v_and_b32_e32 v89, 0xffff, v126
	v_lshrrev_b32_e32 v139, 16, v126
	v_and_b32_e32 v140, 0xffff, v127
	v_lshrrev_b32_e32 v143, 16, v127
	s_waitcnt vmcnt(0)
	v_lshl_or_b32 v89, v128, 16, v89
	v_and_or_b32 v139, v128, s77, v139
	v_lshl_or_b32 v140, v129, 16, v140
	v_and_or_b32 v143, v129, s77, v143
	ds_write_b128 v144, v[80:83]
	ds_write2_b32 v191, v89, v139 offset1:68
	ds_write2_b32 v191, v140, v143 offset0:136 offset1:204
	s_add_i32 s79, s87, 2
	s_cmp_ge_i32 s79, s84
	s_cbranch_scc1 .Lnsa_rsskip
	v_readlane_b32 s74, v254, 48
	v_readfirstlane_b32 s90, v250
	s_movk_i32 s76, 0xb30
	s_movk_i32 s78, 0xbb0
	s_and_b32 s79, s90, 0xff
	s_lshl_b32 s79, s79, 6
	s_add_i32 s79, s79, s74
	s_mulk_i32 s79, 0x1c00
	s_cmpk_lt_u32 s90, 0x100
	s_cselect_b32 s76, s76, 0xc30
	s_cselect_b32 s78, s78, 0xcb0
	s_or_b32 s76, s76, s33
	s_or_b32 s78, s78, s33
	s_lshl_b32 s76, s76, 1
	s_lshl_b32 s78, s78, 1
	s_add_u32 s76, s76, s79
	s_add_u32 s78, s78, s79
	v_readlane_b32 s74, v254, 39
	v_readlane_b32 s75, v254, 40
	s_nop 0
	s_add_u32 s76, s74, s76
	s_addc_u32 s77, s75, 0
	s_add_u32 s78, s74, s78
	s_addc_u32 s79, s75, 0
	global_load_dwordx4 v[80:83], v190, s[76:77]
	global_load_dwordx2 v[126:127], v251, s[78:79]
	global_load_dwordx2 v[128:129], v241, s[78:79]
	v_readlane_b32 s90, v254, 47
